# prep2 V-transposition LDS tiles: row groups offset by 16 B and tiles 9344 B apart so the eight rows of each ds_write_b16 hit different banks
# speedup vs baseline: 1.0063x; 1.0000x over previous
; #define LAS __attribute__((address_space(3)))
; __device__ __forceinline__ int vpos(int k) { return (k & ~12) | ((k & 4) << 1) | ((k & 8) >> 1); }
; __device__ __forceinline__ void nsa_prep2_phase(bf16* z, const float* qg, const float* kg, bf16* vst, bf16* vwt, LAS unsigned char* lds, int tid, int u0, int ustride) {
;     __syncthreads();
;     for (int unit = u0; unit < 256; unit += ustride) {
;         const int b = unit >> 5, tb = unit & 31; const size_t row0 = (size_t)b * SEQ + tb * 64;
;         { const int tok = tid >> 3, ch = tid & 7, pc = vpos(tok);
;     ...
;         { const int tok = tid >> 3, wh = (tid >> 2) & 1, g = tid & 3; norm64_inplace(z + (row0 + tok) * ZP + (wh ? C_KW : C_KS) + g * 64, kg, 1.0f); }
.LBB0_685:
	v_mov_b32_e32 v1, v0
	s_load_dwordx4 s[8:11], s[56:57], 0xb0
	s_lshl_b32 s68, s58, 6
	s_lshl_b64 s[4:5], s[68:69], 2
	v_readlane_b32 s0, v253, 20
	v_readlane_b32 s1, v253, 21
	s_waitcnt lgkmcnt(0)
	s_add_u32 s10, s10, s4
	s_addc_u32 s11, s11, s5
	s_sub_i32 s30, s2, 0x80
	s_lshr_b32 s31, s30, 2
	s_sub_i32 s28, s30, s31
	s_add_i32 s28, s28, -1
	s_and_b64 vcc, exec, s[0:1]
	s_barrier
	s_cbranch_vccz .LBB0_691
	v_ashrrev_i32_e32 v32, 3, v1
	v_lshlrev_b32_e32 v2, 1, v32
	v_lshlrev_b32_e32 v6, 2, v32
	v_and_b32_e32 v5, 7, v1
	v_and_b32_e32 v6, 16, v6
	v_and_b32_e32 v2, 0xffffffe6, v2
	v_add3_u32 v2, 0, v6, v2
	v_and_b32_e32 v6, 8, v32
	v_mul_u32_u24_e32 v7, 0x480, v5
	v_add3_u32 v118, v2, v6, v7
	v_lshl_add_u32 v118, v5, 4, v118
	v_add_u32_e32 v206, 0xff80, v118
	v_and_b32_e32 v2, 4, v1
	v_cmp_eq_u32_e32 vcc, 0, v2
	v_mov_b32_e32 v2, 0x2400
	s_add_u32 s14, s8, s4
	v_cndmask_b32_e32 v2, v2, v223, vcc
	s_movk_i32 s0, 0x400
	v_lshl_add_u64 v[6:7], s[76:77], 0, v[2:3]
	v_lshlrev_b32_e32 v2, 7, v1
	s_addc_u32 s15, s9, s5
	v_ashrrev_i32_e32 v33, 31, v32
	v_cmp_gt_i32_e64 s[8:9], s0, v1
	v_and_b32_e32 v2, 0x180, v2
	v_readlane_b32 s0, v252, 33
	v_lshl_add_u64 v[34:35], v[6:7], 0, v[2:3]
	v_lshlrev_b64 v[6:7], 12, v[32:33]
	v_readlane_b32 s1, v252, 34
	v_mul_lo_u32 v2, v32, s87
	v_lshlrev_b32_e32 v4, 3, v5
	v_lshl_add_u64 v[36:37], s[0:1], 0, v[6:7]
	v_readlane_b32 s0, v252, 35
	v_add_u32_e32 v8, 0, v2
	v_lshlrev_b32_e32 v2, 4, v5
	v_readlane_b32 s1, v252, 36
	v_lshlrev_b32_e32 v119, 6, v1
	v_lshl_add_u64 v[40:41], s[76:77], 0, v[2:3]
	v_lshl_add_u64 v[38:39], s[0:1], 0, v[6:7]
	v_add_u32_e32 v120, v8, v2
	v_lshrrev_b32_e32 v207, 3, v32
	v_lshl_add_u32 v120, v207, 4, v120
	v_lshlrev_b32_e32 v42, 1, v4
	s_mov_b32 s0, s2
	s_branch .LBB0_688
.LBB0_687:
	s_or_b64 exec, exec, s[20:21]
	v_mad_u64_u32 v[4:5], s[4:5], v30, s88, 0
	v_mad_i32_i24 v5, v31, s88, v5
	v_lshl_add_u64 v[44:45], v[34:35], 0, v[4:5]
	global_load_dwordx4 v[130:133], v3, s[10:11]
	global_load_dwordx4 v[134:137], v3, s[10:11] offset:16
	global_load_dwordx4 v[138:141], v3, s[10:11] offset:32
	global_load_dwordx4 v[142:145], v3, s[10:11] offset:48
	global_load_dwordx4 v[146:149], v3, s[10:11] offset:64
	global_load_dwordx4 v[150:153], v3, s[10:11] offset:80
	global_load_dwordx4 v[154:157], v3, s[10:11] offset:96
	global_load_dwordx4 v[158:161], v3, s[10:11] offset:112
	global_load_dwordx4 v[162:165], v3, s[10:11] offset:128
	global_load_dwordx4 v[166:169], v3, s[10:11] offset:144
	global_load_dwordx4 v[170:173], v3, s[10:11] offset:160
	global_load_dwordx4 v[186:189], v3, s[10:11] offset:176
	global_load_dwordx4 v[190:193], v3, s[10:11] offset:192
	global_load_dwordx4 v[194:197], v3, s[10:11] offset:208
	global_load_dwordx4 v[198:201], v3, s[10:11] offset:224
	global_load_dwordx4 v[202:205], v3, s[10:11] offset:240
	global_load_dwordx4 v[8:11], v[44:45], off offset:48
	global_load_dwordx4 v[12:15], v[44:45], off offset:32
	global_load_dwordx4 v[28:31], v[44:45], off
	global_load_dwordx4 v[4:7], v[44:45], off offset:16
	s_lshl_b32 s4, s16, 2
	s_ashr_i32 s5, s4, 31
	s_lshl_b64 s[6:7], s[4:5], 18
	s_lshl_b32 s68, s1, 1
	v_mov_b32_e32 v43, v3
	s_or_b32 s16, s4, 1
	s_ashr_i32 s17, s16, 31
	s_lshl_b64 s[16:17], s[16:17], 18
	s_or_b32 s18, s4, 2
	s_ashr_i32 s19, s18, 31
	s_lshl_b64 s[18:19], s[18:19], 18
	s_or_b32 s4, s4, 3
	s_ashr_i32 s5, s4, 31
	s_lshl_b64 s[4:5], s[4:5], 18
	s_add_i32 s1, s0, 0x80
	s_cmpk_gt_i32 s0, 0x7f
	s_waitcnt vmcnt(3)
	v_lshlrev_b32_e32 v113, 16, v8
	s_waitcnt vmcnt(2)
	v_lshlrev_b32_e32 v58, 16, v12
	v_and_b32_e32 v59, 0xffff0000, v12
	s_waitcnt vmcnt(0)
	v_and_b32_e32 v63, 0xffff0000, v5
	v_and_b32_e32 v62, 0xffff0000, v4
	v_lshlrev_b32_e32 v79, 16, v5
	v_lshlrev_b32_e32 v78, 16, v4
	v_pk_mul_f32 v[4:5], v[62:63], v[62:63]
	v_and_b32_e32 v61, 0xffff0000, v7
	v_and_b32_e32 v60, 0xffff0000, v6
	v_pk_fma_f32 v[4:5], v[78:79], v[78:79], v[4:5]
	v_lshlrev_b32_e32 v81, 16, v7
	v_lshlrev_b32_e32 v80, 16, v6
	v_pk_mul_f32 v[6:7], v[60:61], v[60:61]
	v_pk_add_f32 v[4:5], v[4:5], v[4:5] op_sel:[0,1] op_sel_hi:[1,0]
	v_pk_fma_f32 v[6:7], v[80:81], v[80:81], v[6:7]
	v_lshlrev_b32_e32 v56, 16, v13
	v_pk_add_f32 v[4:5], v[6:7], v[4:5]
	v_and_b32_e32 v57, 0xffff0000, v13
	v_pk_add_f32 v[68:69], v[6:7], v[4:5] op_sel:[1,0] op_sel_hi:[0,1]
	global_load_dwordx4 v[4:7], v[44:45], off offset:112
	global_load_dwordx4 v[16:19], v[44:45], off offset:96
	global_load_dwordx4 v[20:23], v[44:45], off offset:80
	global_load_dwordx4 v[24:27], v[44:45], off offset:64
	v_mul_f32_e32 v2, v59, v59
	v_pk_fma_f32 v[64:65], v[58:59], v[58:59], v[2:3] op_sel_hi:[1,1,0]
	v_mul_f32_e32 v2, v57, v57
	v_pk_fma_f32 v[66:67], v[56:57], v[56:57], v[2:3] op_sel_hi:[1,1,0]
	v_and_b32_e32 v95, 0xffff0000, v31
	v_and_b32_e32 v97, 0xffff0000, v30
	v_and_b32_e32 v101, 0xffff0000, v28
	v_lshlrev_b32_e32 v94, 16, v31
	v_lshlrev_b32_e32 v96, 16, v30
	v_and_b32_e32 v99, 0xffff0000, v29
	v_lshlrev_b32_e32 v100, 16, v28
	v_mov_b32_e32 v30, v97
	v_mov_b32_e32 v31, v101
	v_lshlrev_b32_e32 v98, 16, v29
	v_mov_b32_e32 v28, v96
	v_mov_b32_e32 v29, v100
	v_pk_mul_f32 v[30:31], v[30:31], v[30:31]
	v_mov_b32_e32 v106, v80
	v_pk_fma_f32 v[28:29], v[28:29], v[28:29], v[30:31]
	v_mov_b32_e32 v107, v60
	v_mov_b32_e32 v60, v81
	v_lshlrev_b32_e32 v80, 16, v9
	v_and_b32_e32 v81, 0xffff0000, v9
	v_and_b32_e32 v93, 0xffff0000, v8
	v_and_b32_e32 v92, 0xffff0000, v14
	v_pk_mul_f32 v[8:9], v[80:81], v[80:81]
	v_lshlrev_b32_e32 v112, 16, v14
	v_lshlrev_b32_e32 v115, 16, v10
	v_lshlrev_b32_e32 v114, 16, v15
	v_mov_b32_e32 v110, v78
	v_lshlrev_b32_e32 v78, 16, v11
	v_mov_b32_e32 v65, v8
	v_mov_b32_e32 v67, v9
	v_mov_b32_e32 v111, v62
	v_mov_b32_e32 v62, v79
	v_pk_add_f32 v[8:9], v[64:65], v[66:67]
	v_mov_b32_e32 v104, v112
	v_mov_b32_e32 v105, v92
	s_waitcnt vmcnt(2)
; __device__ __forceinline__ float bflo(unsigned w) { return __uint_as_float(w << 16); }
; __device__ __forceinline__ float bfhi(unsigned w) { return __uint_as_float(w & 0xffff0000u); }
; __device__ __forceinline__ unsigned pk2(float lo, float hi) { return pg8::cvt_pk_bf16(lo, hi); }
; __device__ __forceinline__ void norm64_inplace(bf16* p, const float* gain, float mult) {
;     u32x4 w[8]; float ss = 0.f;
; #pragma unroll
;     for (int k = 0; k < 8; ++k) { w[k] = ((const u32x4*)p)[k];
;         const float a0 = bflo(w[k].x), a1 = bfhi(w[k].x), a2 = bflo(w[k].y), a3 = bfhi(w[k].y), a4 = bflo(w[k].z), a5 = bfhi(w[k].z), a6 = bflo(w[k].w), a7 = bfhi(w[k].w);
;         ss += (a0 * a0 + a1 * a1) + (a2 * a2 + a3 * a3) + (a4 * a4 + a5 * a5) + (a6 * a6 + a7 * a7); }
;     const float r = rsqrtf(ss * (1.0f / 64.0f) + EPS) * mult;
; #pragma unroll
;     for (int k = 0; k < 8; ++k) { const f32x4 g0 = *(const f32x4*)(gain + 8 * k), g1 = *(const f32x4*)(gain + 8 * k + 4);
;         u32x4 o; o.x = pk2(bflo(w[k].x) * r * g0[0], bfhi(w[k].x) * r * g0[1]); o.y = pk2(bflo(w[k].y) * r * g0[2], bfhi(w[k].y) * r * g0[3]);
;         o.z = pk2(bflo(w[k].z) * r * g1[0], bfhi(w[k].z) * r * g1[1]); o.w = pk2(bflo(w[k].w) * r * g1[2], bfhi(w[k].w) * r * g1[3]);
;         ((u32x4*)p)[k] = o; }
	v_and_b32_e32 v47, 0xffff0000, v16
	s_waitcnt vmcnt(1)
	v_and_b32_e32 v51, 0xffff0000, v21
	s_waitcnt vmcnt(0)
	v_and_b32_e32 v55, 0xffff0000, v25
	v_and_b32_e32 v54, 0xffff0000, v24
	v_lshlrev_b32_e32 v83, 16, v25
	v_lshlrev_b32_e32 v82, 16, v24
	v_pk_mul_f32 v[12:13], v[54:55], v[54:55]
	v_and_b32_e32 v53, 0xffff0000, v27
	v_and_b32_e32 v52, 0xffff0000, v26
	v_pk_fma_f32 v[12:13], v[82:83], v[82:83], v[12:13]
	v_lshlrev_b32_e32 v85, 16, v27
	v_lshlrev_b32_e32 v84, 16, v26
	v_pk_mul_f32 v[24:25], v[52:53], v[52:53]
	v_pk_add_f32 v[12:13], v[12:13], v[12:13] op_sel:[0,1] op_sel_hi:[1,0]
	v_pk_fma_f32 v[24:25], v[84:85], v[84:85], v[24:25]
	v_and_b32_e32 v50, 0xffff0000, v20
	v_pk_add_f32 v[12:13], v[24:25], v[12:13]
	v_lshlrev_b32_e32 v87, 16, v21
	v_pk_add_f32 v[70:71], v[24:25], v[12:13] op_sel:[1,0] op_sel_hi:[0,1]
	v_lshlrev_b32_e32 v86, 16, v20
	v_pk_mul_f32 v[12:13], v[50:51], v[50:51]
	v_and_b32_e32 v49, 0xffff0000, v23
	v_and_b32_e32 v48, 0xffff0000, v22
	v_pk_fma_f32 v[12:13], v[86:87], v[86:87], v[12:13]
	v_lshlrev_b32_e32 v89, 16, v23
	v_lshlrev_b32_e32 v88, 16, v22
	v_pk_mul_f32 v[20:21], v[48:49], v[48:49]
	v_pk_add_f32 v[12:13], v[12:13], v[12:13] op_sel:[0,1] op_sel_hi:[1,0]
	v_pk_fma_f32 v[20:21], v[88:89], v[88:89], v[20:21]
	v_lshlrev_b32_e32 v46, 16, v16
	v_pk_add_f32 v[12:13], v[20:21], v[12:13]
	v_mul_f32_e32 v2, v47, v47
	v_pk_add_f32 v[76:77], v[20:21], v[12:13] op_sel:[1,0] op_sel_hi:[0,1]
	s_waitcnt vmcnt(0)
	v_mov_b64_e32 v[20:21], v[134:135]
	v_mov_b64_e32 v[22:23], v[136:137]
	v_mov_b64_e32 v[24:25], v[130:131]
	v_mov_b64_e32 v[26:27], v[132:133]
	v_and_b32_e32 v13, 0xffff0000, v17
	v_pk_fma_f32 v[72:73], v[46:47], v[46:47], v[2:3] op_sel_hi:[1,1,0]
	v_lshlrev_b32_e32 v12, 16, v17
	v_mul_f32_e32 v2, v13, v13
	v_pk_fma_f32 v[74:75], v[12:13], v[12:13], v[2:3] op_sel_hi:[1,1,0]
	v_mul_f32_e32 v2, v95, v95
	v_pk_fma_f32 v[108:109], v[94:95], v[94:95], v[2:3] op_sel_hi:[1,1,0]
	v_mul_f32_e32 v2, v99, v99
	v_pk_fma_f32 v[16:17], v[98:99], v[98:99], v[2:3] op_sel_hi:[1,1,0]
	v_pk_mov_b32 v[102:103], v[18:19], v[6:7] op_sel:[1,0]
	v_pk_add_f32 v[16:17], v[28:29], v[16:17] op_sel:[1,0] op_sel_hi:[0,1]
	v_pk_add_f32 v[30:31], v[28:29], v[16:17]
	v_pk_mov_b32 v[16:17], v[14:15], v[10:11] op_sel:[1,0]
	v_pk_mul_f32 v[14:15], v[92:93], v[92:93]
	v_and_b32_e32 v91, 0xffff0000, v17
	v_and_b32_e32 v90, 0xffff0000, v16
	v_and_b32_e32 v11, 0xffff0000, v11
	v_and_b32_e32 v10, s0, v10
	v_pk_fma_f32 v[116:117], v[112:113], v[112:113], v[14:15]
	v_pk_mul_f32 v[14:15], v[90:91], v[90:91]
	v_mov_b32_e32 v79, v11
	v_pk_mul_f32 v[10:11], v[10:11], v[10:11]
	v_pk_add_f32 v[30:31], v[108:109], v[30:31]
	v_pk_fma_f32 v[122:123], v[114:115], v[114:115], v[14:15]
	v_mul_f32_e32 v31, v78, v78
	v_mov_b32_e32 v69, v11
	v_pk_add_f32 v[8:9], v[116:117], v[8:9]
	v_pk_add_f32 v[10:11], v[30:31], v[68:69]
	v_pk_add_f32 v[8:9], v[122:123], v[8:9]
	v_lshlrev_b32_e32 v29, 16, v6
	v_pk_add_f32 v[8:9], v[10:11], v[8:9]
	v_lshlrev_b32_e32 v6, 16, v7
	v_pk_add_f32 v[108:109], v[8:9], v[8:9] op_sel:[0,1] op_sel_hi:[1,0]
	v_and_b32_e32 v7, 0xffff0000, v7
	v_pk_add_f32 v[70:71], v[108:109], v[70:71]
	v_lshlrev_b32_e32 v15, 16, v4
	v_and_b32_e32 v17, 0xffff0000, v4
	v_mul_f32_e32 v77, v7, v7
	v_mul_f32_e32 v71, v6, v6
	v_lshlrev_b32_e32 v4, 16, v5
	v_and_b32_e32 v5, 0xffff0000, v5
	v_and_b32_e32 v16, 0xffff0000, v18
	v_pk_add_f32 v[70:71], v[70:71], v[76:77]
	v_pk_mul_f32 v[76:77], v[4:5], v[4:5]
	v_lshlrev_b32_e32 v14, 16, v18
	v_lshlrev_b32_e32 v28, 16, v19
	v_and_b32_e32 v19, 0xffff0000, v103
	v_and_b32_e32 v18, 0xffff0000, v102
	v_pk_mul_f32 v[102:103], v[16:17], v[16:17]
	v_mov_b32_e32 v73, v76
	v_mov_b32_e32 v75, v77
	v_pk_fma_f32 v[124:125], v[14:15], v[14:15], v[102:103]
	v_pk_mul_f32 v[102:103], v[18:19], v[18:19]
	v_pk_add_f32 v[72:73], v[72:73], v[74:75]
	v_pk_fma_f32 v[126:127], v[28:29], v[28:29], v[102:103]
	v_pk_add_f32 v[72:73], v[124:125], v[72:73]
	v_mov_b32_e32 v10, v14
	v_pk_add_f32 v[72:73], v[126:127], v[72:73]
	v_mov_b32_e32 v102, v114
	v_pk_add_f32 v[70:71], v[70:71], v[72:73]
	v_mov_b32_e32 v103, v90
	v_add_f32_e32 v2, v70, v71
	v_fmamk_f32 v2, v2, 0x3c800000, v213
	v_cmp_gt_f32_e32 vcc, s83, v2
	v_mul_f32_e32 v14, 0x4b800000, v2
	v_mov_b32_e32 v92, v113
	v_cndmask_b32_e32 v2, v2, v14, vcc
	v_rsq_f32_e32 v2, v2
	v_mov_b32_e32 v90, v115
	v_mov_b32_e32 v68, v82
	v_mov_b32_e32 v69, v54
	v_mul_f32_e32 v14, 0x45800000, v2
	v_cndmask_b32_e32 v2, v2, v14, vcc
	v_pk_mul_f32 v[70:71], v[2:3], v[100:101] op_sel_hi:[0,1]
	v_pk_mul_f32 v[62:63], v[2:3], v[62:63] op_sel_hi:[0,1]
	v_pk_mul_f32 v[58:59], v[2:3], v[58:59] op_sel_hi:[0,1]
	v_pk_mul_f32 v[56:57], v[2:3], v[56:57] op_sel_hi:[0,1]
	v_mov_b32_e32 v54, v83
	v_pk_mul_f32 v[54:55], v[2:3], v[54:55] op_sel_hi:[0,1]
	v_pk_mul_f32 v[24:25], v[24:25], v[70:71]
	v_pk_mul_f32 v[70:71], v[2:3], v[98:99] op_sel_hi:[0,1]
	v_pk_mul_f32 v[26:27], v[26:27], v[70:71]
	v_cvt_pk_bf16_f32 v24, v24, v25
	v_cvt_pk_bf16_f32 v25, v26, v27
	v_pk_mul_f32 v[26:27], v[2:3], v[96:97] op_sel_hi:[0,1]
	v_pk_mul_f32 v[20:21], v[20:21], v[26:27]
	v_pk_mul_f32 v[70:71], v[2:3], v[110:111] op_sel_hi:[0,1]
	v_cvt_pk_bf16_f32 v26, v20, v21
	v_pk_mul_f32 v[20:21], v[2:3], v[94:95] op_sel_hi:[0,1]
	v_pk_mul_f32 v[20:21], v[22:23], v[20:21]
	v_mov_b32_e32 v66, v84
	v_cvt_pk_bf16_f32 v27, v20, v21
	global_store_dwordx4 v[44:45], v[24:27], off
	v_mov_b64_e32 v[20:21], v[142:143]
	v_mov_b64_e32 v[22:23], v[144:145]
	s_nop 0
	v_mov_b64_e32 v[24:25], v[138:139]
	v_mov_b64_e32 v[26:27], v[140:141]
	v_mov_b32_e32 v67, v52
	v_mov_b32_e32 v52, v85
	v_mov_b32_e32 v64, v86
	v_mov_b32_e32 v65, v50
	v_mov_b32_e32 v50, v87
; #define LAS __attribute__((address_space(3)))
; __device__ __forceinline__ float bflo(unsigned w) { return __uint_as_float(w << 16); }
; __device__ __forceinline__ float bfhi(unsigned w) { return __uint_as_float(w & 0xffff0000u); }
; __device__ __forceinline__ unsigned pk2(float lo, float hi) { return pg8::cvt_pk_bf16(lo, hi); }
; __device__ __forceinline__ void norm64_inplace(bf16* p, const float* gain, float mult) {
;     ...
;     for (int k = 0; k < 8; ++k) { const f32x4 g0 = *(const f32x4*)(gain + 8 * k), g1 = *(const f32x4*)(gain + 8 * k + 4);
;         u32x4 o; o.x = pk2(bflo(w[k].x) * r * g0[0], bfhi(w[k].x) * r * g0[1]); o.y = pk2(bflo(w[k].y) * r * g0[2], bfhi(w[k].y) * r * g0[3]);
;         o.z = pk2(bflo(w[k].z) * r * g1[0], bfhi(w[k].z) * r * g1[1]); o.w = pk2(bflo(w[k].w) * r * g1[2], bfhi(w[k].w) * r * g1[3]);
;         ((u32x4*)p)[k] = o; }
; __device__ __forceinline__ void nsa_prep2_phase(bf16* z, const float* qg, const float* kg, bf16* vst, bf16* vwt, LAS unsigned char* lds, int tid, int u0, int ustride) {
;     ...
;         { const int d = tid >> 3, ch = tid & 7;
; #pragma unroll
;           for (int ti = 0; ti < 8; ++ti) { const int g = ti & 3; bf16* dst = (ti >> 2) ? vwt : vst;
;               const u32x4 w = *(const LAS u32x4*)(lds + ti * TILEB + d * TPITCH + ch * 16);
;               *(u32x4*)(dst + ((size_t)(b * 4 + g) * 64 + d) * SEQ + tb * 64 + ch * 8) = w; } }
	v_pk_mul_f32 v[50:51], v[2:3], v[50:51] op_sel_hi:[0,1]
	v_mov_b32_e32 v30, v88
	v_mov_b32_e32 v31, v48
	v_mov_b32_e32 v48, v89
	v_mov_b32_e32 v11, v16
	v_mov_b32_e32 v8, v28
	v_mov_b32_e32 v9, v18
	v_pk_mul_f32 v[12:13], v[2:3], v[12:13] op_sel_hi:[0,1]
	v_pk_mul_f32 v[10:11], v[2:3], v[10:11] op_sel_hi:[0,1]
	v_pk_mul_f32 v[8:9], v[2:3], v[8:9] op_sel_hi:[0,1]
	v_mov_b32_e32 v16, v15
	v_pk_mul_f32 v[4:5], v[2:3], v[4:5] op_sel_hi:[0,1]
	v_mov_b32_e32 v18, v29
	s_mov_b32 s0, s1
	v_pk_mul_f32 v[24:25], v[24:25], v[70:71]
	v_pk_mul_f32 v[26:27], v[26:27], v[62:63]
	v_cvt_pk_bf16_f32 v24, v24, v25
	v_cvt_pk_bf16_f32 v25, v26, v27
	v_pk_mul_f32 v[26:27], v[2:3], v[106:107] op_sel_hi:[0,1]
	v_pk_mul_f32 v[20:21], v[20:21], v[26:27]
	s_nop 0
	v_cvt_pk_bf16_f32 v26, v20, v21
	v_pk_mul_f32 v[20:21], v[2:3], v[60:61] op_sel_hi:[0,1]
	v_pk_mul_f32 v[20:21], v[22:23], v[20:21]
	s_nop 0
	v_cvt_pk_bf16_f32 v27, v20, v21
	global_store_dwordx4 v[44:45], v[24:27], off offset:16
	v_mov_b64_e32 v[20:21], v[150:151]
	v_mov_b64_e32 v[22:23], v[152:153]
	s_nop 0
	v_mov_b64_e32 v[24:25], v[146:147]
	v_mov_b64_e32 v[26:27], v[148:149]
	v_pk_mul_f32 v[24:25], v[24:25], v[58:59]
	v_pk_mul_f32 v[26:27], v[26:27], v[56:57]
	v_cvt_pk_bf16_f32 v24, v24, v25
	v_cvt_pk_bf16_f32 v25, v26, v27
	v_pk_mul_f32 v[26:27], v[2:3], v[104:105] op_sel_hi:[0,1]
	v_pk_mul_f32 v[20:21], v[20:21], v[26:27]
	v_pk_mul_f32 v[56:57], v[2:3], v[92:93] op_sel_hi:[0,1]
	v_cvt_pk_bf16_f32 v26, v20, v21
	v_pk_mul_f32 v[20:21], v[2:3], v[102:103] op_sel_hi:[0,1]
	v_pk_mul_f32 v[20:21], v[22:23], v[20:21]
	s_nop 0
	v_cvt_pk_bf16_f32 v27, v20, v21
	global_store_dwordx4 v[44:45], v[24:27], off offset:32
	v_mov_b64_e32 v[20:21], v[158:159]
	v_mov_b64_e32 v[22:23], v[160:161]
	s_nop 0
	v_mov_b64_e32 v[24:25], v[154:155]
	v_mov_b64_e32 v[26:27], v[156:157]
	v_pk_mul_f32 v[24:25], v[24:25], v[56:57]
	v_pk_mul_f32 v[56:57], v[2:3], v[80:81] op_sel_hi:[0,1]
	v_pk_mul_f32 v[26:27], v[26:27], v[56:57]
	v_cvt_pk_bf16_f32 v24, v24, v25
	v_cvt_pk_bf16_f32 v25, v26, v27
	v_pk_mul_f32 v[26:27], v[2:3], v[90:91] op_sel_hi:[0,1]
	v_pk_mul_f32 v[20:21], v[20:21], v[26:27]
	v_pk_mul_f32 v[56:57], v[2:3], v[68:69] op_sel_hi:[0,1]
	v_cvt_pk_bf16_f32 v26, v20, v21
	v_pk_mul_f32 v[20:21], v[2:3], v[78:79] op_sel_hi:[0,1]
	v_pk_mul_f32 v[20:21], v[22:23], v[20:21]
	s_nop 0
	v_cvt_pk_bf16_f32 v27, v20, v21
	global_store_dwordx4 v[44:45], v[24:27], off offset:48
	v_mov_b64_e32 v[20:21], v[166:167]
	v_mov_b64_e32 v[22:23], v[168:169]
	s_nop 0
	v_mov_b64_e32 v[24:25], v[162:163]
	v_mov_b64_e32 v[26:27], v[164:165]
	v_pk_mul_f32 v[24:25], v[24:25], v[56:57]
	v_pk_mul_f32 v[26:27], v[26:27], v[54:55]
	v_cvt_pk_bf16_f32 v24, v24, v25
	v_cvt_pk_bf16_f32 v25, v26, v27
	v_pk_mul_f32 v[26:27], v[2:3], v[66:67] op_sel_hi:[0,1]
	v_pk_mul_f32 v[20:21], v[20:21], v[26:27]
	s_nop 0
	v_cvt_pk_bf16_f32 v26, v20, v21
	v_pk_mul_f32 v[20:21], v[2:3], v[52:53] op_sel_hi:[0,1]
	v_pk_mul_f32 v[20:21], v[22:23], v[20:21]
	v_pk_mul_f32 v[52:53], v[2:3], v[64:65] op_sel_hi:[0,1]
	v_cvt_pk_bf16_f32 v27, v20, v21
	global_store_dwordx4 v[44:45], v[24:27], off offset:64
	v_mov_b64_e32 v[20:21], v[186:187]
	v_mov_b64_e32 v[22:23], v[188:189]
	s_nop 0
	v_mov_b64_e32 v[24:25], v[170:171]
	v_mov_b64_e32 v[26:27], v[172:173]
	v_pk_mul_f32 v[24:25], v[52:53], v[24:25]
	v_pk_mul_f32 v[26:27], v[50:51], v[26:27]
	v_cvt_pk_bf16_f32 v24, v24, v25
	v_cvt_pk_bf16_f32 v25, v26, v27
	v_pk_mul_f32 v[26:27], v[2:3], v[30:31] op_sel_hi:[0,1]
	v_pk_mul_f32 v[20:21], v[26:27], v[20:21]
	v_pk_mul_f32 v[30:31], v[2:3], v[46:47] op_sel_hi:[0,1]
	v_cvt_pk_bf16_f32 v26, v20, v21
	v_pk_mul_f32 v[20:21], v[2:3], v[48:49] op_sel_hi:[0,1]
	v_pk_mul_f32 v[20:21], v[20:21], v[22:23]
	s_nop 0
	v_cvt_pk_bf16_f32 v27, v20, v21
	global_store_dwordx4 v[44:45], v[24:27], off offset:80
	v_mov_b64_e32 v[20:21], v[194:195]
	v_mov_b64_e32 v[22:23], v[196:197]
	s_nop 0
	v_mov_b64_e32 v[24:25], v[190:191]
	v_mov_b64_e32 v[26:27], v[192:193]
	v_pk_mul_f32 v[10:11], v[10:11], v[20:21]
	v_pk_mul_f32 v[24:25], v[30:31], v[24:25]
	v_pk_mul_f32 v[12:13], v[12:13], v[26:27]
	v_pk_mul_f32 v[8:9], v[8:9], v[22:23]
	v_cvt_pk_bf16_f32 v24, v24, v25
	v_cvt_pk_bf16_f32 v25, v12, v13
	v_cvt_pk_bf16_f32 v26, v10, v11
	v_cvt_pk_bf16_f32 v27, v8, v9
	global_store_dwordx4 v[44:45], v[24:27], off offset:96
	v_mov_b64_e32 v[8:9], v[202:203]
	v_mov_b64_e32 v[10:11], v[204:205]
	v_mov_b64_e32 v[20:21], v[198:199]
	v_mov_b64_e32 v[22:23], v[200:201]
	v_pk_mul_f32 v[12:13], v[2:3], v[16:17] op_sel_hi:[0,1]
	v_pk_mul_f32 v[12:13], v[12:13], v[20:21]
	v_pk_mul_f32 v[4:5], v[4:5], v[22:23]
	v_cvt_pk_bf16_f32 v12, v12, v13
	v_cvt_pk_bf16_f32 v13, v4, v5
	v_pk_mul_f32 v[4:5], v[2:3], v[18:19] op_sel_hi:[0,1]
	v_pk_mul_f32 v[4:5], v[4:5], v[8:9]
	v_lshl_add_u64 v[8:9], v[36:37], 0, s[6:7]
	v_cvt_pk_bf16_f32 v14, v4, v5
	v_pk_mul_f32 v[4:5], v[2:3], v[6:7] op_sel_hi:[0,1]
	v_pk_mul_f32 v[4:5], v[4:5], v[10:11]
	v_lshl_add_u64 v[8:9], v[8:9], 0, s[68:69]
	v_cvt_pk_bf16_f32 v15, v4, v5
	global_store_dwordx4 v[44:45], v[12:15], off offset:112
	s_waitcnt lgkmcnt(0)
	s_barrier
	ds_read_b128 v[4:7], v120
	v_lshl_add_u64 v[8:9], v[8:9], 0, v[42:43]
	s_waitcnt lgkmcnt(0)
	global_store_dwordx4 v[8:9], v[4:7], off
	ds_read_b128 v[4:7], v120 offset:9344
	v_lshl_add_u64 v[8:9], v[36:37], 0, s[16:17]
	v_lshl_add_u64 v[8:9], v[8:9], 0, s[68:69]
	v_lshl_add_u64 v[8:9], v[8:9], 0, v[42:43]
	s_waitcnt lgkmcnt(0)
	global_store_dwordx4 v[8:9], v[4:7], off
	ds_read_b128 v[4:7], v120 offset:18688
	v_lshl_add_u64 v[8:9], v[36:37], 0, s[18:19]
	v_lshl_add_u64 v[8:9], v[8:9], 0, s[68:69]
	v_lshl_add_u64 v[8:9], v[8:9], 0, v[42:43]
	s_waitcnt lgkmcnt(0)
	global_store_dwordx4 v[8:9], v[4:7], off
	ds_read_b128 v[4:7], v120 offset:28032
	v_lshl_add_u64 v[8:9], v[36:37], 0, s[4:5]
	v_lshl_add_u64 v[8:9], v[8:9], 0, s[68:69]
	v_lshl_add_u64 v[8:9], v[8:9], 0, v[42:43]
	s_waitcnt lgkmcnt(0)
	global_store_dwordx4 v[8:9], v[4:7], off
	ds_read_b128 v[4:7], v120 offset:37376
	v_lshl_add_u64 v[8:9], v[38:39], 0, s[6:7]
	v_lshl_add_u64 v[8:9], v[8:9], 0, s[68:69]
	v_lshl_add_u64 v[8:9], v[8:9], 0, v[42:43]
	s_waitcnt lgkmcnt(0)
	global_store_dwordx4 v[8:9], v[4:7], off
	ds_read_b128 v[4:7], v120 offset:46720
	v_lshl_add_u64 v[8:9], v[38:39], 0, s[16:17]
	v_lshl_add_u64 v[8:9], v[8:9], 0, s[68:69]
	v_lshl_add_u64 v[8:9], v[8:9], 0, v[42:43]
	s_waitcnt lgkmcnt(0)
	global_store_dwordx4 v[8:9], v[4:7], off
	ds_read_b128 v[4:7], v120 offset:56064
	v_lshl_add_u64 v[8:9], v[38:39], 0, s[18:19]
	v_lshl_add_u64 v[8:9], v[8:9], 0, s[68:69]
	v_lshl_add_u64 v[8:9], v[8:9], 0, v[42:43]
	s_waitcnt lgkmcnt(0)
	global_store_dwordx4 v[8:9], v[4:7], off
	ds_read_b128 v[4:7], v120 offset:65408
	v_lshl_add_u64 v[8:9], v[38:39], 0, s[4:5]
	v_lshl_add_u64 v[8:9], v[8:9], 0, s[68:69]
	v_lshl_add_u64 v[8:9], v[8:9], 0, v[42:43]
	s_waitcnt lgkmcnt(0)
	global_store_dwordx4 v[8:9], v[4:7], off
	s_barrier
	s_cbranch_scc1 .LBB0_691
; #define LAS __attribute__((address_space(3)))
; __device__ __forceinline__ int vpos(int k) { return (k & ~12) | ((k & 4) << 1) | ((k & 8) >> 1); }
; __device__ __forceinline__ void nsa_prep2_phase(bf16* z, const float* qg, const float* kg, bf16* vst, bf16* vwt, LAS unsigned char* lds, int tid, int u0, int ustride) {
;     ...
;         { const int tok = tid >> 3, ch = tid & 7, pc = vpos(tok);
; #pragma unroll
;           for (int ti = 0; ti < 8; ++ti) { const int g = ti & 3, col = ((ti >> 2) ? C_VW : C_VS) + g * 64 + ch * 8;
;               const u32x4 w = *(const u32x4*)(z + (row0 + tok) * ZP + col);
;               LAS unsigned short* T = (LAS unsigned short*)(lds + ti * TILEB) + pc;
;               T[(ch * 8 + 0) * 72] = (unsigned short)(w.x & 0xffffu); T[(ch * 8 + 1) * 72] = (unsigned short)(w.x >> 16);
;               T[(ch * 8 + 2) * 72] = (unsigned short)(w.y & 0xffffu); T[(ch * 8 + 3) * 72] = (unsigned short)(w.y >> 16);
;               T[(ch * 8 + 4) * 72] = (unsigned short)(w.z & 0xffffu); T[(ch * 8 + 5) * 72] = (unsigned short)(w.z >> 16);
;               T[(ch * 8 + 6) * 72] = (unsigned short)(w.w & 0xffffu); T[(ch * 8 + 7) * 72] = (unsigned short)(w.w >> 16); } }
.LBB0_688:
	s_ashr_i32 s16, s0, 5
	s_ashr_i32 s17, s16, 31
	s_lshl_b32 s1, s0, 6
	s_lshl_b64 s[18:19], s[16:17], 11
	s_and_b32 s1, s1, 0x7c0
	s_or_b32 s18, s18, s1
	v_lshl_add_u64 v[30:31], s[18:19], 0, v[32:33]
	v_mad_u64_u32 v[4:5], s[4:5], v30, s88, v[40:41]
	s_movk_i32 s4, 0x2000
	v_mad_i32_i24 v2, v31, s88, v5
	v_add_co_u32_e32 v4, vcc, s4, v4
	s_nop 1
	v_addc_co_u32_e32 v5, vcc, 0, v2, vcc
	global_load_dwordx4 v[6:9], v[4:5], off offset:512
	global_load_dwordx4 v[10:13], v[4:5], off offset:640
	global_load_dwordx4 v[14:17], v[4:5], off offset:768
	global_load_dwordx4 v[18:21], v[4:5], off offset:896
	global_load_dwordx4 v[22:25], v[4:5], off offset:1536
	global_load_dwordx4 v[26:29], v[4:5], off offset:1664
	s_waitcnt vmcnt(5)
	ds_write_b16 v118, v6
	ds_write_b16_d16_hi v118, v6 offset:144
	ds_write_b16 v118, v7 offset:288
	ds_write_b16_d16_hi v118, v7 offset:432
	ds_write_b16 v118, v8 offset:576
	ds_write_b16_d16_hi v118, v8 offset:720
	ds_write_b16 v118, v9 offset:864
	ds_write_b16_d16_hi v118, v9 offset:1008
	global_load_dwordx4 v[6:9], v[4:5], off offset:1792
	s_waitcnt vmcnt(5)
	ds_write_b16 v118, v10 offset:9344
	ds_write_b16_d16_hi v118, v10 offset:9488
	ds_write_b16 v118, v11 offset:9632
	ds_write_b16_d16_hi v118, v11 offset:9776
	ds_write_b16 v118, v12 offset:9920
	ds_write_b16_d16_hi v118, v12 offset:10064
	ds_write_b16 v118, v13 offset:10208
	ds_write_b16_d16_hi v118, v13 offset:10352
	global_load_dwordx4 v[10:13], v[4:5], off offset:1920
	s_waitcnt vmcnt(5)
	ds_write_b16 v118, v14 offset:18688
	ds_write_b16_d16_hi v118, v14 offset:18832
	ds_write_b16 v118, v15 offset:18976
	ds_write_b16_d16_hi v118, v15 offset:19120
	ds_write_b16 v118, v16 offset:19264
	ds_write_b16_d16_hi v118, v16 offset:19408
	ds_write_b16 v118, v17 offset:19552
	ds_write_b16_d16_hi v118, v17 offset:19696
	s_waitcnt vmcnt(4)
	ds_write_b16 v118, v18 offset:28032
	ds_write_b16_d16_hi v118, v18 offset:28176
	ds_write_b16 v118, v19 offset:28320
	ds_write_b16_d16_hi v118, v19 offset:28464
	ds_write_b16 v118, v20 offset:28608
	ds_write_b16_d16_hi v118, v20 offset:28752
	ds_write_b16 v118, v21 offset:28896
	ds_write_b16_d16_hi v118, v21 offset:29040
	s_waitcnt vmcnt(3)
	ds_write_b16 v118, v22 offset:37376
	ds_write_b16_d16_hi v118, v22 offset:37520
	ds_write_b16 v118, v23 offset:37664
	ds_write_b16_d16_hi v118, v23 offset:37808
	ds_write_b16 v118, v24 offset:37952
	ds_write_b16_d16_hi v118, v24 offset:38096
	ds_write_b16 v118, v25 offset:38240
	ds_write_b16_d16_hi v118, v25 offset:38384
	s_waitcnt vmcnt(2)
	ds_write_b16 v118, v26 offset:46720
	ds_write_b16_d16_hi v118, v26 offset:46864
	ds_write_b16 v118, v27 offset:47008
	ds_write_b16_d16_hi v118, v27 offset:47152
	ds_write_b16 v118, v28 offset:47296
	ds_write_b16_d16_hi v118, v28 offset:47440
	ds_write_b16 v118, v29 offset:47584
	ds_write_b16_d16_hi v118, v29 offset:47728
	s_waitcnt vmcnt(1)
	ds_write_b16 v118, v6 offset:56064
	ds_write_b16_d16_hi v118, v6 offset:56208
	ds_write_b16 v118, v7 offset:56352
	ds_write_b16_d16_hi v118, v7 offset:56496
	ds_write_b16 v118, v8 offset:56640
	ds_write_b16_d16_hi v118, v8 offset:56784
	ds_write_b16 v118, v9 offset:56928
	ds_write_b16_d16_hi v118, v9 offset:57072
	s_waitcnt vmcnt(0)
	ds_write_b16 v206, v10
	ds_write_b16_d16_hi v206, v10 offset:144
	ds_write_b16 v206, v11 offset:288
	ds_write_b16_d16_hi v206, v11 offset:432
	ds_write_b16 v206, v12 offset:576
	ds_write_b16_d16_hi v206, v12 offset:720
	ds_write_b16 v206, v13 offset:864
	ds_write_b16_d16_hi v206, v13 offset:1008
	s_and_saveexec_b64 s[20:21], s[8:9]
	s_cbranch_execz .LBB0_687
	s_mov_b64 s[22:23], 0
	v_mov_b32_e32 v43, v119
	v_mov_b32_e32 v121, v1
